# per-XCD start skew also at P3 entry (same as P5) on the nt + three-class P0 build
# speedup vs baseline: 1.0057x; 1.0057x over previous
.LBB0_567:
	s_xor_b64 s[42:43], s[0:1], -1
	s_lshr_b32 s0, s88, 2
	s_and_b32 s44, s0, 0x3ffffff8
	s_or_b32 s40, s44, s53
	s_lshl_b32 s36, s40, 6
	s_mov_b32 s37, 0
	s_bfe_u32 s52, s88, 0x20003
	s_lshl_b64 s[0:1], s[36:37], 2
	s_add_u32 s0, s96, s0
	s_addc_u32 s1, s97, s1
	s_add_u32 s38, s0, 0x84000
	s_addc_u32 s39, s1, 0
	s_cmp_lt_i32 s76, 4
	s_cselect_b64 s[0:1], -1, 0
	s_and_b64 s[24:25], s[0:1], s[2:3]
	s_andn2_b64 vcc, exec, s[24:25]
	v_lshlrev_b32_e32 v230, 3, v226
	v_lshrrev_b32_e32 v205, 3, v226
	v_and_b32_e32 v228, 31, v226
	v_lshrrev_b32_e32 v229, 5, v227
	v_lshlrev_b32_e32 v192, 4, v226
	s_cbranch_vccnz .LBB0_706
	s_and_b32 s100, s40, 3
